# plus: out-proj tile order, out-proj K-loop LDS reads pipelined, branch GEMMs as continuous ring, row_scales loads issued up front
# speedup vs baseline: 1.0613x; 1.0119x over previous
; DEV float bflo(unsigned w) { return __uint_as_float(w << 16); }
; DEV float bfhi(unsigned w) { return __uint_as_float(w & 0xffff0000u); }
; DEV void row_scales(const u16* __restrict__ zrow0, int col0, int ncol, float* rs, int tid) {
;   if (tid >= 384) return;
;   const int r = tid >> 1, h = tid & 1, lane = tid & 63;
;   const u16* s = zrow0 + (long)r * NINP + col0 + h * (ncol / 2);
;   float ss = 0.f;
;   for (int i = 0; i < ncol / 2; i += 8) {
;     uint4 v = *(const uint4*)(s + i);
;     ss += bflo(v.x) * bflo(v.x) + bfhi(v.x) * bfhi(v.x) + bflo(v.y) * bflo(v.y) + bfhi(v.y) * bfhi(v.y) +
;           bflo(v.z) * bflo(v.z) + bfhi(v.z) * bfhi(v.z) + bflo(v.w) * bflo(v.w) + bfhi(v.w) * bfhi(v.w);
;   }
;   ss += shx(ss, 1, lane);
;   if (h == 0) rs[r] = rsqrtf(ss / (float)ncol + 1e-6f);
; }
; DEV void kvproj_item(const Params& p, int l, int tt, int tf, char* smem, int tid) {
;   const int t0 = tt * 192, f0 = tf * 128;
;   f32x4 acc[2][6];
;   zero_acc<2, 6>(acc);
;   float* rs = (float*)(smem + 122880);
;   __syncthreads();
;   row_scales(p.z + (long)t0 * NINP, C_CKV, 128, rs, tid);
.LBB0_755:
	s_and_b64 vcc, exec, s[6:7]
	s_cbranch_vccz .LBB0_765
	s_add_i32 s6, s15, 0xffb8
	s_and_b32 s7, s6, 0xff
	s_mulk_i32 s7, 0xab
	s_bfe_u32 s11, s7, 0x5000b
	s_mul_i32 s7, s11, 12
	s_sub_i32 s6, s6, s7
	s_and_b32 s6, s6, 0xff
	v_readlane_b32 s7, v255, 10
	s_add_i32 s10, s7, s6
	s_mul_i32 s6, s10, 0x330000
	s_add_u32 s6, s88, s6
	s_movk_i32 s8, 0x180
	s_addc_u32 s7, s89, 0
	v_cmp_gt_i32_e32 vcc, s8, v58
	s_barrier
	s_and_saveexec_b64 s[8:9], vcc
	s_cbranch_execz .LBB0_759
	v_ashrrev_i32_e32 v16, 1, v58
	v_and_b32_e32 v17, 1, v58
	v_mov_b64_e32 v[0:1], s[6:7]
	v_mad_i64_i32 v[0:1], s[16:17], v16, s33, v[0:1]
	v_lshlrev_b32_e32 v156, 7, v17
	s_waitcnt lgkmcnt(0)
	v_lshl_add_u64 v[12:13], v[0:1], 0, v[156:157]
	global_load_dwordx4 v[0:3], v[12:13], off offset:560
	global_load_dwordx4 v[4:7], v[12:13], off offset:544
	global_load_dwordx4 v[8:11], v[12:13], off offset:528
	global_load_dwordx4 v[18:21], v[12:13], off offset:512
	global_load_dwordx4 v[100:103], v[12:13], off offset:624
	global_load_dwordx4 v[104:107], v[12:13], off offset:608
	global_load_dwordx4 v[108:111], v[12:13], off offset:592
	global_load_dwordx4 v[112:115], v[12:13], off offset:576
	v_cmp_eq_u32_e32 vcc, 0, v17
	s_waitcnt vmcnt(4)
	v_and_b32_e32 v15, 0xffff0000, v18
	v_lshlrev_b32_e32 v14, 16, v18
	v_mul_f32_e32 v15, v15, v15
	v_fmac_f32_e32 v15, v14, v14
	v_lshlrev_b32_e32 v14, 16, v19
	v_fmac_f32_e32 v15, v14, v14
	v_and_b32_e32 v14, 0xffff0000, v19
	v_fmac_f32_e32 v15, v14, v14
	v_lshlrev_b32_e32 v14, 16, v20
	v_fmac_f32_e32 v15, v14, v14
	v_and_b32_e32 v14, 0xffff0000, v20
	v_fmac_f32_e32 v15, v14, v14
	v_lshlrev_b32_e32 v14, 16, v21
	v_fmac_f32_e32 v15, v14, v14
	v_and_b32_e32 v14, 0xffff0000, v21
	v_fmac_f32_e32 v15, v14, v14
	v_lshlrev_b32_e32 v14, 16, v8
	v_and_b32_e32 v8, 0xffff0000, v8
	v_mul_f32_e32 v8, v8, v8
	v_fmac_f32_e32 v8, v14, v14
	v_lshlrev_b32_e32 v14, 16, v9
	v_fmac_f32_e32 v8, v14, v14
	v_and_b32_e32 v9, 0xffff0000, v9
	v_fmac_f32_e32 v8, v9, v9
	v_lshlrev_b32_e32 v9, 16, v10
	v_fmac_f32_e32 v8, v9, v9
	v_and_b32_e32 v9, 0xffff0000, v10
	v_fmac_f32_e32 v8, v9, v9
	v_lshlrev_b32_e32 v9, 16, v11
	v_fmac_f32_e32 v8, v9, v9
	v_and_b32_e32 v9, 0xffff0000, v11
	v_fmac_f32_e32 v8, v9, v9
	v_lshlrev_b32_e32 v9, 16, v4
	v_and_b32_e32 v4, 0xffff0000, v4
	v_mul_f32_e32 v4, v4, v4
	v_fmac_f32_e32 v4, v9, v9
	v_lshlrev_b32_e32 v9, 16, v5
	v_fmac_f32_e32 v4, v9, v9
	v_and_b32_e32 v5, 0xffff0000, v5
	v_fmac_f32_e32 v4, v5, v5
	v_lshlrev_b32_e32 v5, 16, v6
	v_fmac_f32_e32 v4, v5, v5
	v_and_b32_e32 v5, 0xffff0000, v6
	v_fmac_f32_e32 v4, v5, v5
	v_lshlrev_b32_e32 v5, 16, v7
	v_fmac_f32_e32 v4, v5, v5
	v_and_b32_e32 v5, 0xffff0000, v7
	v_fmac_f32_e32 v4, v5, v5
	v_lshlrev_b32_e32 v5, 16, v0
	v_and_b32_e32 v0, 0xffff0000, v0
	v_mul_f32_e32 v0, v0, v0
	v_fmac_f32_e32 v0, v5, v5
	v_lshlrev_b32_e32 v5, 16, v1
	v_fmac_f32_e32 v0, v5, v5
	v_and_b32_e32 v1, 0xffff0000, v1
	v_fmac_f32_e32 v0, v1, v1
	v_lshlrev_b32_e32 v1, 16, v2
	v_fmac_f32_e32 v0, v1, v1
	v_and_b32_e32 v1, 0xffff0000, v2
	v_fmac_f32_e32 v0, v1, v1
	v_lshlrev_b32_e32 v1, 16, v3
	v_add_f32_e32 v8, v15, v8
	v_fmac_f32_e32 v0, v1, v1
	v_and_b32_e32 v1, 0xffff0000, v3
	v_add_f32_e32 v4, v8, v4
	v_fmac_f32_e32 v0, v1, v1
	v_add_f32_e32 v18, v4, v0
	s_waitcnt vmcnt(0)
	v_lshlrev_b32_e32 v19, 16, v112
	v_and_b32_e32 v112, 0xffff0000, v112
	v_mul_f32_e32 v112, v112, v112
	v_fmac_f32_e32 v112, v19, v19
	v_lshlrev_b32_e32 v19, 16, v113
	v_fmac_f32_e32 v112, v19, v19
	v_and_b32_e32 v113, 0xffff0000, v113
	v_fmac_f32_e32 v112, v113, v113
	v_lshlrev_b32_e32 v113, 16, v114
	v_fmac_f32_e32 v112, v113, v113
	v_and_b32_e32 v113, 0xffff0000, v114
	v_fmac_f32_e32 v112, v113, v113
	v_lshlrev_b32_e32 v113, 16, v115
	v_fmac_f32_e32 v112, v113, v113
	v_and_b32_e32 v113, 0xffff0000, v115
	v_fmac_f32_e32 v112, v113, v113
	v_lshlrev_b32_e32 v113, 16, v108
	v_and_b32_e32 v108, 0xffff0000, v108
	v_mul_f32_e32 v108, v108, v108
	v_fmac_f32_e32 v108, v113, v113
	v_lshlrev_b32_e32 v113, 16, v109
	v_fmac_f32_e32 v108, v113, v113
	v_and_b32_e32 v109, 0xffff0000, v109
	v_fmac_f32_e32 v108, v109, v109
	v_lshlrev_b32_e32 v109, 16, v110
	v_fmac_f32_e32 v108, v109, v109
	v_and_b32_e32 v109, 0xffff0000, v110
	v_fmac_f32_e32 v108, v109, v109
	v_lshlrev_b32_e32 v109, 16, v111
	v_fmac_f32_e32 v108, v109, v109
	v_and_b32_e32 v109, 0xffff0000, v111
	v_fmac_f32_e32 v108, v109, v109
	v_lshlrev_b32_e32 v109, 16, v104
	v_and_b32_e32 v104, 0xffff0000, v104
	v_mul_f32_e32 v104, v104, v104
	v_fmac_f32_e32 v104, v109, v109
	v_lshlrev_b32_e32 v109, 16, v105
	v_fmac_f32_e32 v104, v109, v109
	v_and_b32_e32 v105, 0xffff0000, v105
	v_fmac_f32_e32 v104, v105, v105
	v_lshlrev_b32_e32 v105, 16, v106
	v_fmac_f32_e32 v104, v105, v105
	v_and_b32_e32 v105, 0xffff0000, v106
	v_fmac_f32_e32 v104, v105, v105
	v_lshlrev_b32_e32 v105, 16, v107
	v_fmac_f32_e32 v104, v105, v105
	v_and_b32_e32 v105, 0xffff0000, v107
	v_fmac_f32_e32 v104, v105, v105
	v_lshlrev_b32_e32 v105, 16, v100
	v_and_b32_e32 v100, 0xffff0000, v100
	v_mul_f32_e32 v100, v100, v100
	v_fmac_f32_e32 v100, v105, v105
	v_lshlrev_b32_e32 v105, 16, v101
	v_fmac_f32_e32 v100, v105, v105
	v_and_b32_e32 v101, 0xffff0000, v101
	v_fmac_f32_e32 v100, v101, v101
	v_lshlrev_b32_e32 v101, 16, v102
	v_fmac_f32_e32 v100, v101, v101
	v_and_b32_e32 v101, 0xffff0000, v102
	v_add_f32_e32 v112, v18, v112
	v_fmac_f32_e32 v100, v101, v101
	v_lshlrev_b32_e32 v101, 16, v103
	v_add_f32_e32 v108, v112, v108
	v_fmac_f32_e32 v100, v101, v101
	v_and_b32_e32 v101, 0xffff0000, v103
	v_add_f32_e32 v104, v108, v104
	v_fmac_f32_e32 v100, v101, v101
	v_lshlrev_b32_e32 v1, 2, v58
	v_add_f32_e32 v0, v104, v100
	v_bitop3_b32 v1, v1, 4, v252 bitop3:0x6c
	ds_bpermute_b32 v1, v1, v0
	s_and_b64 exec, exec, vcc
	s_cbranch_execz .LBB0_759
	s_waitcnt lgkmcnt(0)
	v_add_f32_e32 v0, v0, v1
	v_fmamk_f32 v0, v0, 0x3c000000, v196
	s_mov_b32 s16, 0x800000
	v_mul_f32_e32 v1, 0x4b800000, v0
	v_cmp_gt_f32_e32 vcc, s16, v0
	s_nop 1
	v_cndmask_b32_e32 v0, v0, v1, vcc
	v_rsq_f32_e32 v0, v0
	s_nop 0
	v_mul_f32_e32 v1, 0x45800000, v0
	v_cndmask_b32_e32 v0, v0, v1, vcc
	v_mov_b32_e32 v1, 0x1e000
	v_lshl_add_u32 v1, v16, 2, v1
	ds_write_b32 v1, v0

; DEV float bflo(unsigned w) { return __uint_as_float(w << 16); }
; DEV float bfhi(unsigned w) { return __uint_as_float(w & 0xffff0000u); }
; DEV void row_scales(const u16* __restrict__ zrow0, int col0, int ncol, float* rs, int tid) {
;   if (tid >= 384) return;
;   const int r = tid >> 1, h = tid & 1, lane = tid & 63;
;   const u16* s = zrow0 + (long)r * NINP + col0 + h * (ncol / 2);
;   float ss = 0.f;
;   for (int i = 0; i < ncol / 2; i += 8) {
;     uint4 v = *(const uint4*)(s + i);
;     ss += bflo(v.x) * bflo(v.x) + bfhi(v.x) * bfhi(v.x) + bflo(v.y) * bflo(v.y) + bfhi(v.y) * bfhi(v.y) +
;           bflo(v.z) * bflo(v.z) + bfhi(v.z) * bfhi(v.z) + bflo(v.w) * bflo(v.w) + bfhi(v.w) * bfhi(v.w);
;   }
;   ss += shx(ss, 1, lane);
;   if (h == 0) rs[r] = rsqrtf(ss / (float)ncol + 1e-6f);
; }
.LBB0_770:
	s_waitcnt lgkmcnt(0)
	global_load_dwordx4 v[64:67], v[0:1], off offset:-12
	global_load_dwordx4 v[68:71], v[0:1], off offset:-28
	global_load_dwordx4 v[72:75], v[0:1], off offset:-44
	global_load_dwordx4 v[76:79], v[0:1], off offset:-60
	global_load_dwordx4 v[80:83], v[0:1], off offset:52
	global_load_dwordx4 v[84:87], v[0:1], off offset:36
	global_load_dwordx4 v[88:91], v[0:1], off offset:20
	global_load_dwordx4 v[92:95], v[0:1], off offset:4
	global_load_dwordx4 v[96:99], v[0:1], off offset:116
	global_load_dwordx4 v[100:103], v[0:1], off offset:100
	global_load_dwordx4 v[104:107], v[0:1], off offset:84
	global_load_dwordx4 v[108:111], v[0:1], off offset:68
	global_load_dwordx4 v[112:115], v[0:1], off offset:180
	global_load_dwordx4 v[116:119], v[0:1], off offset:164
	global_load_dwordx4 v[120:123], v[0:1], off offset:148
	global_load_dwordx4 v[124:127], v[0:1], off offset:132
	s_waitcnt vmcnt(12)
	v_lshlrev_b32_e32 v22, 16, v76
	v_and_b32_e32 v23, 0xffff0000, v76
	v_pk_mul_f32 v[22:23], v[22:23], v[22:23]
	v_lshlrev_b32_e32 v25, 16, v77
	v_and_b32_e32 v24, 0xffff0000, v77
	v_pk_mul_f32 v[76:77], v[24:25], v[24:25]
	v_add_f32_e32 v5, v22, v23
	v_lshlrev_b32_e32 v25, 16, v78
	v_and_b32_e32 v24, 0xffff0000, v78
	v_add_f32_e32 v5, v5, v77
	v_pk_mul_f32 v[24:25], v[24:25], v[24:25]
	v_add_f32_e32 v5, v76, v5
	v_lshlrev_b32_e32 v27, 16, v79
	v_and_b32_e32 v26, 0xffff0000, v79
	v_add_f32_e32 v5, v25, v5
	v_pk_mul_f32 v[78:79], v[26:27], v[26:27]
	v_add_f32_e32 v5, v24, v5
	v_add_f32_e32 v5, v79, v5
	v_add_f32_e32 v5, v78, v5
	v_add_f32_e32 v22, v4, v5
	v_lshlrev_b32_e32 v4, 16, v72
	v_and_b32_e32 v5, 0xffff0000, v72
	v_pk_mul_f32 v[4:5], v[4:5], v[4:5]
	v_lshlrev_b32_e32 v77, 16, v73
	v_and_b32_e32 v76, 0xffff0000, v73
	v_pk_mul_f32 v[72:73], v[76:77], v[76:77]
	v_add_f32_e32 v4, v4, v5
	v_lshlrev_b32_e32 v77, 16, v74
	v_and_b32_e32 v76, 0xffff0000, v74
	v_add_f32_e32 v4, v4, v73
	v_pk_mul_f32 v[76:77], v[76:77], v[76:77]
	v_add_f32_e32 v4, v72, v4
	v_lshlrev_b32_e32 v79, 16, v75
	v_and_b32_e32 v78, 0xffff0000, v75
	v_add_f32_e32 v4, v77, v4
	v_pk_mul_f32 v[74:75], v[78:79], v[78:79]
	v_add_f32_e32 v4, v76, v4
	v_add_f32_e32 v4, v75, v4
	v_add_f32_e32 v4, v74, v4
	v_add_f32_e32 v76, v22, v4
	v_lshlrev_b32_e32 v4, 16, v68
	v_and_b32_e32 v5, 0xffff0000, v68
	v_pk_mul_f32 v[4:5], v[4:5], v[4:5]
	v_lshlrev_b32_e32 v73, 16, v69
	v_and_b32_e32 v72, 0xffff0000, v69
	v_pk_mul_f32 v[68:69], v[72:73], v[72:73]
	v_add_f32_e32 v4, v4, v5
	v_lshlrev_b32_e32 v73, 16, v70
	v_and_b32_e32 v72, 0xffff0000, v70
	v_add_f32_e32 v4, v4, v69
	v_pk_mul_f32 v[72:73], v[72:73], v[72:73]
	v_add_f32_e32 v4, v68, v4
	v_lshlrev_b32_e32 v75, 16, v71
	v_and_b32_e32 v74, 0xffff0000, v71
	v_add_f32_e32 v4, v73, v4
	v_pk_mul_f32 v[70:71], v[74:75], v[74:75]
	v_add_f32_e32 v4, v72, v4
	v_add_f32_e32 v4, v71, v4
	v_add_f32_e32 v4, v70, v4
	v_add_f32_e32 v72, v76, v4
	v_lshlrev_b32_e32 v4, 16, v64
	v_and_b32_e32 v5, 0xffff0000, v64
	v_pk_mul_f32 v[4:5], v[4:5], v[4:5]
	v_lshlrev_b32_e32 v69, 16, v65
	v_and_b32_e32 v68, 0xffff0000, v65
	v_pk_mul_f32 v[64:65], v[68:69], v[68:69]
	v_add_f32_e32 v4, v4, v5
	v_lshlrev_b32_e32 v69, 16, v66
	v_and_b32_e32 v68, 0xffff0000, v66
	v_add_f32_e32 v4, v4, v65
	v_pk_mul_f32 v[68:69], v[68:69], v[68:69]
	v_add_f32_e32 v4, v64, v4
	v_lshlrev_b32_e32 v71, 16, v67
	v_and_b32_e32 v70, 0xffff0000, v67
	v_add_f32_e32 v4, v69, v4
	v_pk_mul_f32 v[66:67], v[70:71], v[70:71]
	v_add_f32_e32 v4, v68, v4
	v_add_f32_e32 v4, v67, v4
	v_add_f32_e32 v4, v66, v4
	v_add_f32_e32 v4, v72, v4
	s_waitcnt vmcnt(8)
	v_lshlrev_b32_e32 v22, 16, v92
	v_and_b32_e32 v23, 0xffff0000, v92
	v_pk_mul_f32 v[22:23], v[22:23], v[22:23]
	v_lshlrev_b32_e32 v25, 16, v93
	v_and_b32_e32 v24, 0xffff0000, v93
	v_pk_mul_f32 v[92:93], v[24:25], v[24:25]
	v_add_f32_e32 v5, v22, v23
	v_lshlrev_b32_e32 v25, 16, v94
	v_and_b32_e32 v24, 0xffff0000, v94
	v_add_f32_e32 v5, v5, v93
	v_pk_mul_f32 v[24:25], v[24:25], v[24:25]
	v_add_f32_e32 v5, v92, v5
	v_lshlrev_b32_e32 v27, 16, v95
	v_and_b32_e32 v26, 0xffff0000, v95
	v_add_f32_e32 v5, v25, v5
	v_pk_mul_f32 v[94:95], v[26:27], v[26:27]
	v_add_f32_e32 v5, v24, v5
	v_add_f32_e32 v5, v95, v5
	v_add_f32_e32 v5, v94, v5
	v_add_f32_e32 v22, v4, v5
	v_lshlrev_b32_e32 v4, 16, v88
	v_and_b32_e32 v5, 0xffff0000, v88
	v_pk_mul_f32 v[4:5], v[4:5], v[4:5]
	v_lshlrev_b32_e32 v93, 16, v89
	v_and_b32_e32 v92, 0xffff0000, v89
	v_pk_mul_f32 v[88:89], v[92:93], v[92:93]
	v_add_f32_e32 v4, v4, v5
	v_lshlrev_b32_e32 v93, 16, v90
	v_and_b32_e32 v92, 0xffff0000, v90
	v_add_f32_e32 v4, v4, v89
	v_pk_mul_f32 v[92:93], v[92:93], v[92:93]
	v_add_f32_e32 v4, v88, v4
	v_lshlrev_b32_e32 v95, 16, v91
	v_and_b32_e32 v94, 0xffff0000, v91
	v_add_f32_e32 v4, v93, v4
	v_pk_mul_f32 v[90:91], v[94:95], v[94:95]
	v_add_f32_e32 v4, v92, v4
	v_add_f32_e32 v4, v91, v4
	v_add_f32_e32 v4, v90, v4
	v_add_f32_e32 v92, v22, v4
	v_lshlrev_b32_e32 v4, 16, v84
	v_and_b32_e32 v5, 0xffff0000, v84
	v_pk_mul_f32 v[4:5], v[4:5], v[4:5]
	v_lshlrev_b32_e32 v89, 16, v85
	v_and_b32_e32 v88, 0xffff0000, v85
	v_pk_mul_f32 v[84:85], v[88:89], v[88:89]
	v_add_f32_e32 v4, v4, v5
	v_lshlrev_b32_e32 v89, 16, v86
	v_and_b32_e32 v88, 0xffff0000, v86
	v_add_f32_e32 v4, v4, v85
	v_pk_mul_f32 v[88:89], v[88:89], v[88:89]
	v_add_f32_e32 v4, v84, v4
	v_lshlrev_b32_e32 v91, 16, v87
	v_and_b32_e32 v90, 0xffff0000, v87
	v_add_f32_e32 v4, v89, v4
	v_pk_mul_f32 v[86:87], v[90:91], v[90:91]
	v_add_f32_e32 v4, v88, v4
	v_add_f32_e32 v4, v87, v4
	v_add_f32_e32 v4, v86, v4
	v_add_f32_e32 v88, v92, v4
	v_lshlrev_b32_e32 v4, 16, v80
	v_and_b32_e32 v5, 0xffff0000, v80
	v_pk_mul_f32 v[4:5], v[4:5], v[4:5]
	v_lshlrev_b32_e32 v85, 16, v81
	v_and_b32_e32 v84, 0xffff0000, v81
	v_pk_mul_f32 v[80:81], v[84:85], v[84:85]
	v_add_f32_e32 v4, v4, v5
	v_lshlrev_b32_e32 v85, 16, v82
	v_and_b32_e32 v84, 0xffff0000, v82
	v_add_f32_e32 v4, v4, v81
	v_pk_mul_f32 v[84:85], v[84:85], v[84:85]
	v_add_f32_e32 v4, v80, v4
	v_lshlrev_b32_e32 v87, 16, v83
	v_and_b32_e32 v86, 0xffff0000, v83
	v_add_f32_e32 v4, v85, v4
	v_pk_mul_f32 v[82:83], v[86:87], v[86:87]
	v_add_f32_e32 v4, v84, v4
	v_add_f32_e32 v4, v83, v4
	v_add_f32_e32 v4, v82, v4
	v_add_f32_e32 v4, v88, v4
	s_waitcnt vmcnt(4)
; DEV float bflo(unsigned w) { return __uint_as_float(w << 16); }
; DEV float bfhi(unsigned w) { return __uint_as_float(w & 0xffff0000u); }
; DEV void row_scales(const u16* __restrict__ zrow0, int col0, int ncol, float* rs, int tid) {
;   if (tid >= 384) return;
;   const int r = tid >> 1, h = tid & 1, lane = tid & 63;
;   const u16* s = zrow0 + (long)r * NINP + col0 + h * (ncol / 2);
;   float ss = 0.f;
;   for (int i = 0; i < ncol / 2; i += 8) {
;     uint4 v = *(const uint4*)(s + i);
;     ss += bflo(v.x) * bflo(v.x) + bfhi(v.x) * bfhi(v.x) + bflo(v.y) * bflo(v.y) + bfhi(v.y) * bfhi(v.y) +
;           bflo(v.z) * bflo(v.z) + bfhi(v.z) * bfhi(v.z) + bflo(v.w) * bflo(v.w) + bfhi(v.w) * bfhi(v.w);
;   }
;   ss += shx(ss, 1, lane);
;   if (h == 0) rs[r] = rsqrtf(ss / (float)ncol + 1e-6f);
; }
	v_lshlrev_b32_e32 v22, 16, v108
	v_and_b32_e32 v23, 0xffff0000, v108
	v_pk_mul_f32 v[22:23], v[22:23], v[22:23]
	v_lshlrev_b32_e32 v25, 16, v109
	v_and_b32_e32 v24, 0xffff0000, v109
	v_pk_mul_f32 v[108:109], v[24:25], v[24:25]
	v_add_f32_e32 v5, v22, v23
	v_lshlrev_b32_e32 v25, 16, v110
	v_and_b32_e32 v24, 0xffff0000, v110
	v_add_f32_e32 v5, v5, v109
	v_pk_mul_f32 v[24:25], v[24:25], v[24:25]
	v_add_f32_e32 v5, v108, v5
	v_lshlrev_b32_e32 v27, 16, v111
	v_and_b32_e32 v26, 0xffff0000, v111
	v_add_f32_e32 v5, v25, v5
	v_pk_mul_f32 v[110:111], v[26:27], v[26:27]
	v_add_f32_e32 v5, v24, v5
	v_add_f32_e32 v5, v111, v5
	v_add_f32_e32 v5, v110, v5
	v_add_f32_e32 v22, v4, v5
	v_lshlrev_b32_e32 v4, 16, v104
	v_and_b32_e32 v5, 0xffff0000, v104
	v_pk_mul_f32 v[4:5], v[4:5], v[4:5]
	v_lshlrev_b32_e32 v109, 16, v105
	v_and_b32_e32 v108, 0xffff0000, v105
	v_pk_mul_f32 v[104:105], v[108:109], v[108:109]
	v_add_f32_e32 v4, v4, v5
	v_lshlrev_b32_e32 v109, 16, v106
	v_and_b32_e32 v108, 0xffff0000, v106
	v_add_f32_e32 v4, v4, v105
	v_pk_mul_f32 v[108:109], v[108:109], v[108:109]
	v_add_f32_e32 v4, v104, v4
	v_lshlrev_b32_e32 v111, 16, v107
	v_and_b32_e32 v110, 0xffff0000, v107
	v_add_f32_e32 v4, v109, v4
	v_pk_mul_f32 v[106:107], v[110:111], v[110:111]
	v_add_f32_e32 v4, v108, v4
	v_add_f32_e32 v4, v107, v4
	v_add_f32_e32 v4, v106, v4
	v_add_f32_e32 v108, v22, v4
	v_lshlrev_b32_e32 v4, 16, v100
	v_and_b32_e32 v5, 0xffff0000, v100
	v_pk_mul_f32 v[4:5], v[4:5], v[4:5]
	v_lshlrev_b32_e32 v105, 16, v101
	v_and_b32_e32 v104, 0xffff0000, v101
	v_pk_mul_f32 v[100:101], v[104:105], v[104:105]
	v_add_f32_e32 v4, v4, v5
	v_lshlrev_b32_e32 v105, 16, v102
	v_and_b32_e32 v104, 0xffff0000, v102
	v_add_f32_e32 v4, v4, v101
	v_pk_mul_f32 v[104:105], v[104:105], v[104:105]
	v_add_f32_e32 v4, v100, v4
	v_lshlrev_b32_e32 v107, 16, v103
	v_and_b32_e32 v106, 0xffff0000, v103
	v_add_f32_e32 v4, v105, v4
	v_pk_mul_f32 v[102:103], v[106:107], v[106:107]
	v_add_f32_e32 v4, v104, v4
	v_add_f32_e32 v4, v103, v4
	v_add_f32_e32 v4, v102, v4
	v_add_f32_e32 v104, v108, v4
	v_lshlrev_b32_e32 v4, 16, v96
	v_and_b32_e32 v5, 0xffff0000, v96
	v_pk_mul_f32 v[4:5], v[4:5], v[4:5]
	v_lshlrev_b32_e32 v101, 16, v97
	v_and_b32_e32 v100, 0xffff0000, v97
	v_pk_mul_f32 v[96:97], v[100:101], v[100:101]
	v_add_f32_e32 v4, v4, v5
	v_lshlrev_b32_e32 v101, 16, v98
	v_and_b32_e32 v100, 0xffff0000, v98
	v_add_f32_e32 v4, v4, v97
	v_pk_mul_f32 v[100:101], v[100:101], v[100:101]
	v_add_f32_e32 v4, v96, v4
	v_lshlrev_b32_e32 v103, 16, v99
	v_and_b32_e32 v102, 0xffff0000, v99
	v_add_f32_e32 v4, v101, v4
	v_pk_mul_f32 v[98:99], v[102:103], v[102:103]
	v_add_f32_e32 v4, v100, v4
	v_add_f32_e32 v4, v99, v4
	v_add_f32_e32 v4, v98, v4
	v_add_f32_e32 v4, v104, v4
	s_waitcnt vmcnt(0)
	v_lshlrev_b32_e32 v22, 16, v124
	v_and_b32_e32 v23, 0xffff0000, v124
	v_pk_mul_f32 v[22:23], v[22:23], v[22:23]
	v_lshlrev_b32_e32 v25, 16, v125
	v_and_b32_e32 v24, 0xffff0000, v125
	v_pk_mul_f32 v[124:125], v[24:25], v[24:25]
	v_add_f32_e32 v5, v22, v23
	v_lshlrev_b32_e32 v25, 16, v126
	v_and_b32_e32 v24, 0xffff0000, v126
	v_add_f32_e32 v5, v5, v125
	v_pk_mul_f32 v[24:25], v[24:25], v[24:25]
	v_add_f32_e32 v5, v124, v5
	v_lshlrev_b32_e32 v27, 16, v127
	v_and_b32_e32 v26, 0xffff0000, v127
	v_add_f32_e32 v5, v25, v5
	v_pk_mul_f32 v[126:127], v[26:27], v[26:27]
	v_add_f32_e32 v5, v24, v5
	v_add_f32_e32 v5, v127, v5
	v_add_f32_e32 v5, v126, v5
	v_add_f32_e32 v22, v4, v5
	v_lshlrev_b32_e32 v4, 16, v120
	v_and_b32_e32 v5, 0xffff0000, v120
	v_pk_mul_f32 v[4:5], v[4:5], v[4:5]
	v_lshlrev_b32_e32 v125, 16, v121
	v_and_b32_e32 v124, 0xffff0000, v121
	v_pk_mul_f32 v[120:121], v[124:125], v[124:125]
	v_add_f32_e32 v4, v4, v5
	v_lshlrev_b32_e32 v125, 16, v122
	v_and_b32_e32 v124, 0xffff0000, v122
	v_add_f32_e32 v4, v4, v121
	v_pk_mul_f32 v[124:125], v[124:125], v[124:125]
	v_add_f32_e32 v4, v120, v4
	v_lshlrev_b32_e32 v127, 16, v123
	v_and_b32_e32 v126, 0xffff0000, v123
	v_add_f32_e32 v4, v125, v4
	v_pk_mul_f32 v[122:123], v[126:127], v[126:127]
	v_add_f32_e32 v4, v124, v4
	v_add_f32_e32 v4, v123, v4
	v_add_f32_e32 v4, v122, v4
	v_add_f32_e32 v124, v22, v4
	v_lshlrev_b32_e32 v4, 16, v116
	v_and_b32_e32 v5, 0xffff0000, v116
	v_pk_mul_f32 v[4:5], v[4:5], v[4:5]
	v_lshlrev_b32_e32 v121, 16, v117
	v_and_b32_e32 v120, 0xffff0000, v117
	v_pk_mul_f32 v[116:117], v[120:121], v[120:121]
	v_add_f32_e32 v4, v4, v5
	v_lshlrev_b32_e32 v121, 16, v118
	v_and_b32_e32 v120, 0xffff0000, v118
	v_add_f32_e32 v4, v4, v117
	v_pk_mul_f32 v[120:121], v[120:121], v[120:121]
	v_add_f32_e32 v4, v116, v4
	v_lshlrev_b32_e32 v123, 16, v119
	v_and_b32_e32 v122, 0xffff0000, v119
	v_add_f32_e32 v4, v121, v4
	v_pk_mul_f32 v[118:119], v[122:123], v[122:123]
	v_add_f32_e32 v4, v120, v4
	v_add_f32_e32 v4, v119, v4
	v_add_f32_e32 v4, v118, v4
	v_add_f32_e32 v120, v124, v4
	v_lshlrev_b32_e32 v4, 16, v112
	v_and_b32_e32 v5, 0xffff0000, v112
	v_pk_mul_f32 v[4:5], v[4:5], v[4:5]
	v_lshlrev_b32_e32 v117, 16, v113
	v_and_b32_e32 v116, 0xffff0000, v113
	v_pk_mul_f32 v[112:113], v[116:117], v[116:117]
	v_add_f32_e32 v4, v4, v5
	v_lshlrev_b32_e32 v117, 16, v114
	v_and_b32_e32 v116, 0xffff0000, v114
	v_add_f32_e32 v4, v4, v113
	v_pk_mul_f32 v[116:117], v[116:117], v[116:117]
	v_add_f32_e32 v4, v112, v4
	v_lshlrev_b32_e32 v119, 16, v115
	v_and_b32_e32 v118, 0xffff0000, v115
	v_add_f32_e32 v4, v117, v4
	v_pk_mul_f32 v[114:115], v[118:119], v[118:119]
	v_add_f32_e32 v4, v116, v4
	v_add_f32_e32 v4, v115, v4
	v_add_f32_e32 v4, v114, v4
	v_add_f32_e32 v4, v120, v4
	v_lshlrev_b32_e32 v0, 2, v58
	v_bitop3_b32 v0, v0, 4, v252 bitop3:0x6c
	ds_bpermute_b32 v0, v0, v4
	v_cmp_eq_u32_e32 vcc, 0, v3
	s_and_b64 exec, exec, vcc
	s_cbranch_execz .LBB0_773
	s_waitcnt lgkmcnt(0)
	v_add_f32_e32 v0, v4, v0
	v_fmamk_f32 v0, v0, 0x3b800000, v196
	s_mov_b32 s11, 0x800000
	v_mul_f32_e32 v1, 0x4b800000, v0
	v_cmp_gt_f32_e32 vcc, s11, v0
	s_nop 1
	v_cndmask_b32_e32 v0, v0, v1, vcc
	v_rsq_f32_e32 v0, v0
	s_nop 0
	v_mul_f32_e32 v1, 0x45800000, v0
	v_cndmask_b32_e32 v0, v0, v1, vcc
	v_mov_b32_e32 v1, 0x1e000
	v_lshl_add_u32 v1, v2, 2, v1
	ds_write_b32 v1, v0

; DEV float bflo(unsigned w) { return __uint_as_float(w << 16); }
; DEV float bfhi(unsigned w) { return __uint_as_float(w & 0xffff0000u); }
; template <int WT>
; DEV void branch_item(const Params& p, int l, int t0, int tf, char* smem, int tid) {
;     ...
; #pragma unroll
;     for (int n = 0; n < 2; ++n) {
; #pragma unroll
;       for (int t = 0; t < WT; ++t) {
;         const uint2 gz = PREG ? gzr[n][PREG ? t : 0]
;                               : *(const uint2*)(p.z + (long)(t0 + wt * (WT * 16) + t * 16 + fr) * NINP + C_BRG + br * 1024 + f0 + wn * 32 + n * 16 + fq * 4);
;         mg[n][t][0] += bflo(gz.x) * acc[n][t][0];
;         mg[n][t][1] += bfhi(gz.x) * acc[n][t][1];
;         mg[n][t][2] += bflo(gz.y) * acc[n][t][2];
;         mg[n][t][3] += bfhi(gz.y) * acc[n][t][3];
;       }
;     }
;   }
.LBB0_1182:
	s_waitcnt vmcnt(10)
	v_lshlrev_b32_e32 v176, 16, v164
	v_and_b32_e32 v177, 0xffff0000, v164
	v_pk_fma_f32 v[136:137], v[44:45], v[176:177], v[136:137]
	v_lshlrev_b32_e32 v44, 16, v165
	v_and_b32_e32 v45, 0xffff0000, v165
	v_pk_fma_f32 v[138:139], v[46:47], v[44:45], v[138:139]
	v_lshlrev_b32_e32 v44, 16, v162
	v_and_b32_e32 v45, 0xffff0000, v162
	v_pk_fma_f32 v[126:127], v[40:41], v[44:45], v[126:127]
	v_lshlrev_b32_e32 v40, 16, v163
	v_and_b32_e32 v41, 0xffff0000, v163
	v_pk_fma_f32 v[128:129], v[42:43], v[40:41], v[128:129]
	v_lshlrev_b32_e32 v40, 16, v160
	v_and_b32_e32 v41, 0xffff0000, v160
	v_pk_fma_f32 v[120:121], v[36:37], v[40:41], v[120:121]
	v_lshlrev_b32_e32 v36, 16, v161
	v_and_b32_e32 v37, 0xffff0000, v161
	v_pk_fma_f32 v[122:123], v[38:39], v[36:37], v[122:123]
	v_lshlrev_b32_e32 v36, 16, v158
	v_and_b32_e32 v37, 0xffff0000, v158
	v_pk_fma_f32 v[116:117], v[32:33], v[36:37], v[116:117]
	v_lshlrev_b32_e32 v32, 16, v159
	v_and_b32_e32 v33, 0xffff0000, v159
	v_pk_fma_f32 v[118:119], v[34:35], v[32:33], v[118:119]
	v_lshlrev_b32_e32 v32, 16, v154
	v_and_b32_e32 v33, 0xffff0000, v154
	v_pk_fma_f32 v[110:111], v[28:29], v[32:33], v[110:111]
	v_lshlrev_b32_e32 v28, 16, v155
	v_and_b32_e32 v29, 0xffff0000, v155
	v_pk_fma_f32 v[112:113], v[30:31], v[28:29], v[112:113]
	v_lshlrev_b32_e32 v28, 16, v152
	v_and_b32_e32 v29, 0xffff0000, v152
	v_pk_fma_f32 v[106:107], v[24:25], v[28:29], v[106:107]
	v_lshlrev_b32_e32 v24, 16, v153
	v_and_b32_e32 v25, 0xffff0000, v153
	v_pk_fma_f32 v[108:109], v[26:27], v[24:25], v[108:109]
	v_lshlrev_b32_e32 v24, 16, v150
	v_and_b32_e32 v25, 0xffff0000, v150
	v_pk_fma_f32 v[98:99], v[20:21], v[24:25], v[98:99]
	v_lshlrev_b32_e32 v20, 16, v151
	v_and_b32_e32 v21, 0xffff0000, v151
	v_pk_fma_f32 v[102:103], v[22:23], v[20:21], v[102:103]
	v_lshlrev_b32_e32 v20, 16, v148
	v_and_b32_e32 v21, 0xffff0000, v148
	v_pk_fma_f32 v[94:95], v[16:17], v[20:21], v[94:95]
	v_lshlrev_b32_e32 v16, 16, v149
	v_and_b32_e32 v17, 0xffff0000, v149
	v_pk_fma_f32 v[100:101], v[18:19], v[16:17], v[100:101]
	v_lshlrev_b32_e32 v16, 16, v146
	v_and_b32_e32 v17, 0xffff0000, v146
	v_pk_fma_f32 v[90:91], v[8:9], v[16:17], v[90:91]
	v_lshlrev_b32_e32 v8, 16, v147
	v_and_b32_e32 v9, 0xffff0000, v147
	v_pk_fma_f32 v[96:97], v[10:11], v[8:9], v[96:97]
	v_lshlrev_b32_e32 v8, 16, v144
	v_and_b32_e32 v9, 0xffff0000, v144
	v_pk_fma_f32 v[84:85], v[4:5], v[8:9], v[84:85]
	v_lshlrev_b32_e32 v4, 16, v145
	v_and_b32_e32 v5, 0xffff0000, v145
	v_pk_fma_f32 v[92:93], v[6:7], v[4:5], v[92:93]
	v_lshlrev_b32_e32 v4, 16, v142
	v_and_b32_e32 v5, 0xffff0000, v142
	v_pk_fma_f32 v[80:81], v[0:1], v[4:5], v[80:81]
	v_lshlrev_b32_e32 v0, 16, v143
	v_and_b32_e32 v1, 0xffff0000, v143
	v_pk_fma_f32 v[86:87], v[2:3], v[0:1], v[86:87]
	v_lshlrev_b32_e32 v0, 16, v140
	v_and_b32_e32 v1, 0xffff0000, v140
	v_pk_fma_f32 v[78:79], v[12:13], v[0:1], v[78:79]
	v_lshlrev_b32_e32 v0, 16, v141
	v_and_b32_e32 v1, 0xffff0000, v141
	s_add_i32 s7, s7, 1
	v_pk_fma_f32 v[82:83], v[14:15], v[0:1], v[82:83]
	v_lshl_add_u64 v[88:89], v[88:89], 0, s[96:97]
	v_lshl_add_u64 v[104:105], v[104:105], 0, s[96:97]
	v_lshl_add_u64 v[114:115], v[114:115], 0, s[96:97]
	v_lshl_add_u64 v[124:125], v[124:125], 0, s[4:5]
	s_cmp_lg_u32 s7, 3
	v_lshl_add_u64 v[130:131], v[130:131], 0, s[4:5]
	s_cbranch_scc0 .LBB0_1180
; template <int WN, int WT>
; DEV void gemm_mainloop(const u16* __restrict__ Wt, long ldw, const u16* __restrict__ A, long lda, int K,
;                        char* smem, int tid, f32x4 (&acc)[WN][WT]) {
;     ...
;   const int nk = K >> 6;
;   __syncthreads();
;   stage_tile<NR>(Wt, ldw, 0, smem, tid);
;   stage_tile<TR>(A, lda, 0, smem + WB, tid);
;   if (nk > 1) {
;     stage_tile<NR>(Wt, ldw, 64, smem + STG, tid);
;     stage_tile<TR>(A, lda, 64, smem + STG + WB, tid);
;   }
; template <int WT>
; DEV void branch_item(const Params& p, int l, int t0, int tf, char* smem, int tid) {
;     ...
;   for (int br = 0; br < 3; ++br) {
;     f32x4 acc[2][WT];
;     zero_acc<2, WT>(acc);
;     constexpr bool PREG = (WT <= 6);
;     uint2 gzr[2][PREG ? WT : 1];
;     if (PREG) {
; #pragma unroll
;       for (int n = 0; n < 2; ++n)
; #pragma unroll
;         for (int t = 0; t < (PREG ? WT : 1); ++t)
;           gzr[n][t] = *(const uint2*)(p.z + (long)(t0 + wt * (WT * 16) + t * 16 + fr) * NINP + C_BRG + br * 1024 + f0 + wn * 32 + n * 16 + fq * 4);
;     }
;     gemm_mainloop<2, WT>(p.WbrT + ((long)(l * 3 + br) * 1024 + f0) * 512, 512, p.Y + ((long)br * TG + t0) * 512, 512, 512, smem, tid, acc);
.LBB0_1183:
	s_lshl_b32 s24, s7, 11
	s_mul_i32 s10, s14, 3
	v_lshl_add_u64 v[0:1], v[62:63], 0, s[24:25]
	v_lshl_add_u64 v[2:3], v[64:65], 0, s[24:25]
	v_lshl_add_u64 v[4:5], v[66:67], 0, s[24:25]
	v_lshl_add_u64 v[6:7], v[68:69], 0, s[24:25]
	v_lshl_add_u64 v[8:9], v[70:71], 0, s[24:25]
	v_lshl_add_u64 v[10:11], v[72:73], 0, s[24:25]
	s_add_i32 s24, s7, s10
	s_lshl_b64 s[10:11], s[24:25], 20
	s_mul_i32 s12, s7, 0x4800
	s_add_u32 s12, s12, s8
	global_load_dwordx2 v[164:165], v[0:1], off
	global_load_dwordx2 v[162:163], v[2:3], off
	global_load_dwordx2 v[148:149], v[2:3], off offset:32
	global_load_dwordx2 v[150:151], v[0:1], off offset:32
	global_load_dwordx2 v[160:161], v[4:5], off
	global_load_dwordx2 v[158:159], v[6:7], off
	global_load_dwordx2 v[144:145], v[6:7], off offset:32
	global_load_dwordx2 v[146:147], v[4:5], off offset:32
	global_load_dwordx2 v[154:155], v[8:9], off
	global_load_dwordx2 v[152:153], v[10:11], off
	global_load_dwordx2 v[140:141], v[10:11], off offset:32
	global_load_dwordx2 v[142:143], v[8:9], off offset:32
	s_addc_u32 s13, 0, s9
	s_cmp_lg_u32 s7, 0
	s_cbranch_scc1 .Lp5a_skipstage
	v_lshl_add_u64 v[0:1], v[74:75], 0, s[10:11]
	v_readfirstlane_b32 s10, v168
	s_lshl_b64 s[12:13], s[12:13], 10
	v_lshl_add_u64 v[2:3], v[0:1], 0, v[132:133]
	s_mov_b32 m0, s10
	v_readfirstlane_b32 s10, v169
	v_add_u32_e32 v8, 0x4000, v168
	s_barrier
	global_load_lds_dwordx4 v[2:3], off
	v_lshl_add_u64 v[0:1], v[0:1], 0, v[134:135]
	s_mov_b32 m0, s10
	v_lshl_add_u64 v[4:5], v[76:77], 0, s[12:13]
	v_readfirstlane_b32 s10, v8
	v_add_u32_e32 v10, 0x4000, v169
	global_load_lds_dwordx4 v[0:1], off
	v_lshl_add_u64 v[6:7], v[4:5], 0, v[132:133]
	s_mov_b32 m0, s10
	v_readfirstlane_b32 s10, v10
	v_add_u32_e32 v10, 0x4000, v170
	global_load_lds_dwordx4 v[6:7], off
	v_lshl_add_u64 v[8:9], v[4:5], 0, v[134:135]
	s_mov_b32 m0, s10
	v_readfirstlane_b32 s10, v10
	v_add_u32_e32 v10, 0xa000, v168
	global_load_lds_dwordx4 v[8:9], off
	v_lshl_add_u64 v[4:5], v[60:61], 1, v[4:5]
	s_mov_b32 m0, s10
	v_readfirstlane_b32 s10, v10
	global_load_lds_dwordx4 v[4:5], off
	v_lshl_add_u64 v[2:3], v[2:3], 0, s[34:35]
	s_mov_b32 m0, s10
	v_lshl_add_u64 v[0:1], v[0:1], 0, s[34:35]
	global_load_lds_dwordx4 v[2:3], off
	v_add_u32_e32 v2, 0xa000, v169
	s_mov_b32 s16, 0
	v_readfirstlane_b32 s10, v2
	v_add_u32_e32 v2, 0xe000, v168
	s_mov_b32 m0, s10
	v_readfirstlane_b32 s10, v2
	v_add_u32_e32 v2, 0xe000, v169
	global_load_lds_dwordx4 v[0:1], off
	v_lshl_add_u64 v[0:1], v[6:7], 0, s[34:35]
	s_mov_b32 m0, s10
	v_readfirstlane_b32 s10, v2
	v_add_u32_e32 v2, 0xe000, v170
	global_load_lds_dwordx4 v[0:1], off
	v_lshl_add_u64 v[0:1], v[8:9], 0, s[34:35]
	s_mov_b32 m0, s10
	v_readfirstlane_b32 s10, v2
	global_load_lds_dwordx4 v[0:1], off
	v_lshl_add_u64 v[0:1], v[4:5], 0, s[34:35]
	s_mov_b32 m0, s10
	s_mov_b64 s[10:11], 0
	global_load_lds_dwordx4 v[0:1], off
	s_mov_b32 s17, 0
	s_branch .Lp5a_zero
.Lp5a_skipstage:
	s_mov_b64 s[10:11], 0
	s_mov_b32 s17, 0
.Lp5a_zero:
	v_mov_b32_e32 v12, 0
	v_mov_b32_e32 v13, v156
	v_mov_b32_e32 v14, v156
	v_mov_b32_e32 v15, v156
	v_mov_b32_e32 v0, 0
	v_mov_b32_e32 v1, v156
	v_mov_b32_e32 v2, v156
	v_mov_b32_e32 v3, v156
	v_mov_b32_e32 v4, 0
	v_mov_b32_e32 v5, v156
	v_mov_b32_e32 v6, v156
	v_mov_b32_e32 v7, v156
	v_mov_b32_e32 v8, 0
	v_mov_b32_e32 v9, v156
	v_mov_b32_e32 v10, v156
	v_mov_b32_e32 v11, v156
	v_mov_b32_e32 v16, 0
	v_mov_b32_e32 v17, v156
	v_mov_b32_e32 v18, v156
	v_mov_b32_e32 v19, v156
	v_mov_b32_e32 v20, 0
	v_mov_b32_e32 v21, v156
	v_mov_b32_e32 v22, v156
	v_mov_b32_e32 v23, v156
	v_mov_b32_e32 v24, 0
	v_mov_b32_e32 v25, v156
	v_mov_b32_e32 v26, v156
	v_mov_b32_e32 v27, v156
	v_mov_b32_e32 v28, 0
	v_mov_b32_e32 v29, v156
	v_mov_b32_e32 v30, v156
	v_mov_b32_e32 v31, v156
	v_mov_b32_e32 v32, 0
	v_mov_b32_e32 v33, v156
	v_mov_b32_e32 v34, v156
	v_mov_b32_e32 v35, v156
	v_mov_b32_e32 v36, 0
	v_mov_b32_e32 v37, v156
	v_mov_b32_e32 v38, v156
	v_mov_b32_e32 v39, v156
	v_mov_b32_e32 v40, 0
	v_mov_b32_e32 v41, v156
	v_mov_b32_e32 v42, v156
	v_mov_b32_e32 v43, v156
	v_mov_b32_e32 v44, 0
	v_mov_b32_e32 v45, v156
	v_mov_b32_e32 v46, v156
	v_mov_b32_e32 v47, v156
	s_branch .LBB0_1185

; template <int WN, int WT>
; DEV void gemm_mainloop(const u16* __restrict__ Wt, long ldw, const u16* __restrict__ A, long lda, int K,
;                        char* smem, int tid, f32x4 (&acc)[WN][WT]) {
;     ...
;     if (kt + 1 < nk) asm volatile("s_waitcnt vmcnt(%0)" ::"n"(NLD) : "memory");
;     else asm volatile("s_waitcnt vmcnt(0)" ::: "memory");
;     __builtin_amdgcn_s_barrier();
;     asm volatile("" ::: "memory");
;     if (kt + 2 < nk) {
;       int nx = cur + 2;
;       if (nx >= 3) nx -= 3;
;       char* nbuf = smem + nx * STG;
;       stage_tile<NR>(Wt, ldw, (kt + 2) * 64, nbuf, tid);
;       stage_tile<TR>(A, lda, (kt + 2) * 64, nbuf + WB, tid);
;     }
; template <int WT>
; DEV void branch_item(const Params& p, int l, int t0, int tf, char* smem, int tid) {
;     ...
;   for (int br = 0; br < 3; ++br) {
;     f32x4 acc[2][WT];
;     zero_acc<2, WT>(acc);
;     constexpr bool PREG = (WT <= 6);
;     uint2 gzr[2][PREG ? WT : 1];
;     if (PREG) {
; #pragma unroll
;       for (int n = 0; n < 2; ++n)
; #pragma unroll
;         for (int t = 0; t < (PREG ? WT : 1); ++t)
;           gzr[n][t] = *(const uint2*)(p.z + (long)(t0 + wt * (WT * 16) + t * 16 + fr) * NINP + C_BRG + br * 1024 + f0 + wn * 32 + n * 16 + fq * 4);
;     }
;     gemm_mainloop<2, WT>(p.WbrT + ((long)(l * 3 + br) * 1024 + f0) * 512, 512, p.Y + ((long)br * TG + t0) * 512, 512, 512, smem, tid, acc);
.LBB0_1185:
	s_cmp_gt_u32 s17, 6
	s_cbranch_scc0 .Lp5a_h1
	s_cmp_eq_u32 s7, 2
	s_cbranch_scc0 .Lp5a_w5
	s_waitcnt vmcnt(0)
	s_branch .LBB0_1189
.Lp5a_h1:
	s_cmp_gt_u32 s17, 1
	s_cbranch_scc1 .Lp5a_w5
	s_cmp_eq_u32 s7, 0
	s_cbranch_scc1 .Lp5a_w5
	s_waitcnt vmcnt(17)
	s_branch .LBB0_1189
.Lp5a_w5:
	s_waitcnt vmcnt(5)
.LBB0_1189:
	s_barrier
	s_cmp_gt_u32 s17, 5
	s_cbranch_scc0 .Lp5a_dma_norm
	s_cmp_eq_u32 s7, 2
	s_cbranch_scc1 .LBB0_1184
	s_add_u32 s62, s10, 0xffc00
	s_addc_u32 s63, s11, 0
	s_add_u32 s64, s10, 0x11ffc00
	s_addc_u32 s65, s11, 0
	s_branch .Lp5a_dma
.Lp5a_dma_norm:
	s_mov_b64 s[62:63], s[10:11]
	s_mov_b64 s[64:65], s[10:11]
.Lp5a_dma:
	s_cmp_gt_i32 s16, 0
	s_cselect_b32 s12, -1, 2
	s_add_i32 s12, s12, s16
	s_mul_i32 s12, s12, 0xa000
	v_add_u32_e32 v175, s12, v168
	v_add_u32_e32 v178, s12, v169
	v_readfirstlane_b32 s13, v175
	v_lshl_add_u64 v[176:177], v[130:131], 0, s[62:63]
	s_mov_b32 m0, s13
	v_readfirstlane_b32 s13, v178
	v_add_u32_e32 v175, 0x4000, v175
	global_load_lds_dwordx4 v[176:177], off
	v_lshl_add_u64 v[176:177], v[124:125], 0, s[62:63]
	s_mov_b32 m0, s13
	v_readfirstlane_b32 s13, v175
	v_add_u32_e32 v175, 0x4000, v178
	global_load_lds_dwordx4 v[176:177], off
	s_mov_b32 m0, s13
	v_readfirstlane_b32 s13, v175
	v_add_u32_e32 v175, s12, v170
	v_lshl_add_u64 v[176:177], v[114:115], 0, s[64:65]
	v_add_u32_e32 v175, 0x4000, v175
	global_load_lds_dwordx4 v[176:177], off
	v_lshl_add_u64 v[176:177], v[104:105], 0, s[64:65]
	s_mov_b32 m0, s13
	v_readfirstlane_b32 s12, v175
	global_load_lds_dwordx4 v[176:177], off
	v_lshl_add_u64 v[176:177], v[88:89], 0, s[64:65]
	s_mov_b32 m0, s12
	s_nop 0
	global_load_lds_dwordx4 v[176:177], off
	s_branch .LBB0_1184

; #define OPQ int tid = tid0; asm volatile("" : "+v"(tid));
; template <int WT>
; DEV void outproj_item(const Params& p, int l, int g, int t0, int tf, char* smem, int tid) {
;   const int f0 = tf * 128;
;   const int wid = tid >> 6, lane = tid & 63, fr = lane & 15, fq = lane >> 4, wn = wid & 3, wt = wid >> 2;
;   f32x4 acc[2][WT];
;   zero_acc<2, WT>(acc);
;   const int bl = t0 / NTOK, j0 = t0 % NTOK, b = g * G + bl;
;   const float* gate_c = p.mod + ((long)l * 33 + 32) * 3072 + 2048;
;   const float* gate_l = p.mod + ((long)l * 33 + b) * 3072 + 2048;
;   const float* hc = (l == 0 ? p.ctx : p.hctx) + (long)b * NCTX * D;
;   const float* hl = (l == 0 ? p.x : p.out) + (long)b * SEQ * D;
;   float4 hpre[2][WT];
; #pragma unroll
;   for (int n = 0; n < 2; ++n)
; #pragma unroll
;     for (int t = 0; t < WT; ++t) {
;       const int f = f0 + wn * 32 + n * 16 + fq * 4;
;       const int j = j0 + wt * (WT * 16) + t * 16 + fr;
;       hpre[n][t] = *(const float4*)(j < NCTX ? hc + (long)j * D + f : hl + (long)(j - NCTX) * D + f);
;     }
;   gemm_mainloop<2, WT>(p.WoutT + ((long)l * 1024 + f0) * 1024, 1024, p.mg + (long)t0 * 1024, 1024, 1024, smem, tid, acc);
; __global__ void __launch_bounds__(512) mega(Params p, int coop) {
;     ...
;         for (int j = xr; j < 96; j += xper) { OPQ outproj_item<6>(p, l, g, (xx * 12 + j % 12) * 192, j / 12, smem, tid); }
.LBB0_1261:
	s_and_b32 s8, s57, 7
	s_ashr_i32 s9, s57, 3
	v_readlane_b32 s10, v255, 10
	s_add_i32 s9, s9, s10
	s_mul_i32 s16, s9, 0xc0
	s_lshl_b32 s18, s8, 7
	s_sext_i32_i16 s8, s16
	s_mulk_i32 s8, 0xe39
	s_lshr_b32 s9, s8, 31
	s_ashr_i32 s8, s8, 23
	s_add_i32 s8, s8, s9
	s_and_b32 s9, s8, 0xffff
	s_mulk_i32 s8, 0x900
	s_sub_i32 s8, s16, s8
	s_sext_i32_i16 s17, s8
	v_readlane_b32 s8, v255, 29
	v_mov_b32_e32 v40, v197
	s_add_i32 s24, s8, s9
	s_lshl_b64 s[8:9], s[24:25], 20
	v_bfe_u32 v43, v40, 4, 2
	v_lshrrev_b32_e32 v0, 1, v40
	s_add_u32 s12, s53, s8
	v_and_b32_e32 v45, 0x60, v0
	v_lshlrev_b32_e32 v0, 2, v43
	v_and_b32_e32 v41, 15, v40
	s_addc_u32 s13, s52, s9
	s_lshl_b64 s[10:11], s[24:25], 23
	v_or3_b32 v110, v0, v45, s18
	v_lshrrev_b32_e32 v44, 8, v40
	s_add_u32 s40, s55, s10
	v_or_b32_e32 v0, s17, v41
	s_movk_i32 s17, 0x60
	v_ashrrev_i32_e32 v111, 31, v110
	s_addc_u32 s41, s54, s11
	v_mad_i32_i24 v8, v44, s17, v0
	v_lshlrev_b64 v[96:97], 2, v[110:111]
	v_lshl_add_u64 v[0:1], s[40:41], 0, v[96:97]
	v_add_u32_e32 v4, 0xffffff00, v8
	v_ashrrev_i32_e32 v5, 31, v8
	v_cmp_gt_i32_e64 s[40:41], s72, v8
	v_lshl_add_u64 v[2:3], s[12:13], 0, v[96:97]
	s_movk_i32 s12, 0xf0
	v_cndmask_b32_e64 v5, 0, v5, s[40:41]
	v_cndmask_b32_e64 v4, v4, v8, s[40:41]
	v_cndmask_b32_e64 v7, v1, v3, s[40:41]
	v_cndmask_b32_e64 v6, v0, v2, s[40:41]
	v_lshlrev_b64 v[108:109], 12, v[4:5]
	v_lshl_add_u64 v[4:5], v[6:7], 0, v[108:109]
	global_load_dwordx4 v[48:51], v[4:5], off
	v_or_b32_e32 v4, 16, v8
	v_ashrrev_i32_e32 v5, 31, v4
	v_add_u32_e32 v6, 0xffffff10, v8
	v_cmp_gt_i32_e64 s[42:43], s12, v8
	s_movk_i32 s12, 0xe0
	v_cmp_gt_i32_e64 s[44:45], s12, v8
	v_cndmask_b32_e64 v5, 0, v5, s[42:43]
	v_cndmask_b32_e64 v4, v6, v4, s[42:43]
	v_cndmask_b32_e64 v7, v1, v3, s[42:43]
	v_cndmask_b32_e64 v6, v0, v2, s[42:43]
	v_lshlrev_b64 v[98:99], 12, v[4:5]
	v_lshl_add_u64 v[4:5], v[6:7], 0, v[98:99]
	global_load_dwordx4 v[52:55], v[4:5], off
	v_add_u32_e32 v4, 32, v8
	v_ashrrev_i32_e32 v5, 31, v4
	v_add_u32_e32 v6, 0xffffff20, v8
	v_cndmask_b32_e64 v5, 0, v5, s[44:45]
	v_cndmask_b32_e64 v4, v6, v4, s[44:45]
	v_cndmask_b32_e64 v7, v1, v3, s[44:45]
	v_cndmask_b32_e64 v6, v0, v2, s[44:45]
	v_lshlrev_b64 v[100:101], 12, v[4:5]
	v_lshl_add_u64 v[4:5], v[6:7], 0, v[100:101]
	global_load_dwordx4 v[56:59], v[4:5], off
	v_add_u32_e32 v4, 48, v8
	s_movk_i32 s12, 0xd0
	v_ashrrev_i32_e32 v5, 31, v4
	v_add_u32_e32 v6, 0xffffff30, v8
	v_cmp_gt_i32_e64 s[46:47], s12, v8
	s_movk_i32 s12, 0xc0
	v_cmp_gt_i32_e64 s[48:49], s12, v8
	v_cndmask_b32_e64 v5, 0, v5, s[46:47]
	v_cndmask_b32_e64 v4, v6, v4, s[46:47]
	v_cndmask_b32_e64 v7, v1, v3, s[46:47]
	v_cndmask_b32_e64 v6, v0, v2, s[46:47]
	v_lshlrev_b64 v[102:103], 12, v[4:5]
	v_lshl_add_u64 v[4:5], v[6:7], 0, v[102:103]
	global_load_dwordx4 v[60:63], v[4:5], off
	v_add_u32_e32 v4, 64, v8
	v_ashrrev_i32_e32 v5, 31, v4
	v_add_u32_e32 v6, 0xffffff40, v8
	v_cndmask_b32_e64 v5, 0, v5, s[48:49]
	v_cndmask_b32_e64 v4, v6, v4, s[48:49]
	v_cndmask_b32_e64 v7, v1, v3, s[48:49]
	v_cndmask_b32_e64 v6, v0, v2, s[48:49]
	v_lshlrev_b64 v[104:105], 12, v[4:5]
	v_lshl_add_u64 v[4:5], v[6:7], 0, v[104:105]
	global_load_dwordx4 v[64:67], v[4:5], off
	v_add_u32_e32 v4, 0x50, v8
	v_ashrrev_i32_e32 v5, 31, v4
	v_add_u32_e32 v6, 0xffffff50, v8
	v_cmp_gt_i32_e64 s[50:51], s21, v8
	v_lshrrev_b32_e32 v42, 4, v40
	s_ashr_i32 s19, s18, 31
	v_cndmask_b32_e64 v5, 0, v5, s[50:51]
	v_cndmask_b32_e64 v4, v6, v4, s[50:51]
	v_cndmask_b32_e64 v7, v1, v3, s[50:51]
	v_cndmask_b32_e64 v6, v0, v2, s[50:51]
	v_lshlrev_b64 v[106:107], 12, v[4:5]
	v_lshl_add_u64 v[4:5], v[6:7], 0, v[106:107]
	v_lshl_add_u64 v[0:1], v[0:1], 0, 64
	v_lshl_add_u64 v[2:3], v[2:3], 0, 64
	global_load_dwordx4 v[68:71], v[4:5], off
	v_cndmask_b32_e64 v5, v1, v3, s[40:41]
	v_cndmask_b32_e64 v4, v0, v2, s[40:41]
	v_lshl_add_u64 v[4:5], v[4:5], 0, v[108:109]
	global_load_dwordx4 v[20:23], v[4:5], off
	v_cndmask_b32_e64 v5, v1, v3, s[42:43]
	v_cndmask_b32_e64 v4, v0, v2, s[42:43]
	v_lshl_add_u64 v[4:5], v[4:5], 0, v[98:99]
	global_load_dwordx4 v[16:19], v[4:5], off
	v_cndmask_b32_e64 v5, v1, v3, s[44:45]
	v_cndmask_b32_e64 v4, v0, v2, s[44:45]
	v_lshl_add_u64 v[4:5], v[4:5], 0, v[100:101]
	s_lshl_b64 s[18:19], s[18:19], 11
	v_xor_b32_e32 v24, v42, v40
	global_load_dwordx4 v[12:15], v[4:5], off
	v_cndmask_b32_e64 v5, v1, v3, s[46:47]
	v_cndmask_b32_e64 v4, v0, v2, s[46:47]
	s_add_u32 s12, s15, s18
	v_lshlrev_b32_e32 v24, 4, v24
	v_ashrrev_i32_e32 v26, 3, v40
	v_add_u32_e32 v32, 0x200, v40
	v_lshl_add_u64 v[4:5], v[4:5], 0, v[102:103]
	s_addc_u32 s13, s56, s19
	s_ashr_i32 s17, s16, 31
	v_readlane_b32 s60, v254, 62
	v_and_b32_e32 v156, 0x70, v24
	v_ashrrev_i32_e32 v27, 31, v26
	v_lshlrev_b32_e32 v111, 4, v40
	v_ashrrev_i32_e32 v30, 3, v32
	global_load_dwordx4 v[8:11], v[4:5], off
	v_cndmask_b32_e64 v5, v1, v3, s[48:49]
	v_cndmask_b32_e64 v4, v0, v2, s[48:49]
	v_cndmask_b32_e64 v1, v1, v3, s[50:51]
	v_cndmask_b32_e64 v0, v0, v2, s[50:51]
	s_lshl_b64 s[16:17], s[16:17], 11
	v_readlane_b32 s62, v255, 0
	v_lshl_add_u64 v[24:25], s[12:13], 0, v[156:157]
	v_lshlrev_b64 v[26:27], 11, v[26:27]
	v_readfirstlane_b32 s12, v111
	v_ashrrev_i32_e32 v31, 31, v30
	v_lshlrev_b32_e32 v122, 4, v32
	v_lshl_add_u64 v[4:5], v[4:5], 0, v[104:105]
	v_lshl_add_u64 v[0:1], v[0:1], 0, v[106:107]
	v_readlane_b32 s63, v255, 1
	s_add_u32 s58, s62, s16
	v_lshl_add_u64 v[28:29], v[24:25], 0, v[26:27]
	s_mov_b32 m0, s12
	v_lshlrev_b64 v[30:31], 11, v[30:31]
	v_readfirstlane_b32 s12, v122
	v_add_u32_e32 v36, 0x4000, v111
	global_load_dwordx4 v[4:7], v[4:5], off
	s_addc_u32 s59, s63, s17
	global_load_dwordx4 v[0:3], v[0:1], off
	s_barrier
; template <int WN, int WT>
; DEV void gemm_mainloop(const u16* __restrict__ Wt, long ldw, const u16* __restrict__ A, long lda, int K,
;                        char* smem, int tid, f32x4 (&acc)[WN][WT]) {
;     ...
;   __syncthreads();
;   stage_tile<NR>(Wt, ldw, 0, smem, tid);
;   stage_tile<TR>(A, lda, 0, smem + WB, tid);
;   if (nk > 1) {
;     stage_tile<NR>(Wt, ldw, 64, smem + STG, tid);
;     stage_tile<TR>(A, lda, 64, smem + STG + WB, tid);
;   }
;   int cur = 0;
; #pragma nounroll
;   for (int kt = 0; kt < nk; ++kt) {
;     if (kt + 1 < nk) asm volatile("s_waitcnt vmcnt(%0)" ::"n"(NLD) : "memory");
;     else asm volatile("s_waitcnt vmcnt(0)" ::: "memory");
;     __builtin_amdgcn_s_barrier();
;     asm volatile("" ::: "memory");
;     if (kt + 2 < nk) {
;       int nx = cur + 2;
;       if (nx >= 3) nx -= 3;
;       char* nbuf = smem + nx * STG;
;       stage_tile<NR>(Wt, ldw, (kt + 2) * 64, nbuf, tid);
;       stage_tile<TR>(A, lda, (kt + 2) * 64, nbuf + WB, tid);
;     }
;     const char* wb = smem + cur * STG;
;     const char* ab = wb + WB;
; #pragma unroll
;     for (int ks = 0; ks < 2; ++ks) {
;       bf16x8 wf[WN], af[WT];
; #pragma unroll
;       for (int n = 0; n < WN; ++n) wf[n] = lds_frag(wb, wn * (WN * 16) + n * 16 + fr, ks * 4 + fq);
; #pragma unroll
;       for (int t = 0; t < WT; ++t) af[t] = lds_frag(ab, wt * (WT * 16) + t * 16 + fr, ks * 4 + fq);
; #pragma unroll
;       for (int n = 0; n < WN; ++n)
; #pragma unroll
;         for (int t = 0; t < WT; ++t)
;           acc[n][t] = __builtin_amdgcn_mfma_f32_16x16x32_bf16(wf[n], af[t], acc[n][t], 0, 0, 0);
;     }
;     cur = (cur == 2) ? 0 : cur + 1;
;   }
	global_load_lds_dwordx4 v[28:29], off
	v_lshl_add_u64 v[24:25], v[24:25], 0, v[30:31]
	s_mov_b32 m0, s12
	v_readfirstlane_b32 s12, v36
	v_add_u32_e32 v38, 0x4000, v122
	v_add_u32_e32 v46, 0x400, v40
	global_load_lds_dwordx4 v[24:25], off
	v_lshl_add_u64 v[32:33], s[58:59], 0, v[156:157]
	s_mov_b32 m0, s12
	v_readfirstlane_b32 s12, v38
	v_ashrrev_i32_e32 v38, 3, v46
	v_lshlrev_b32_e32 v123, 4, v46
	v_lshl_add_u64 v[34:35], v[32:33], 0, v[26:27]
	v_ashrrev_i32_e32 v39, 31, v38
	v_add_u32_e32 v46, 0x4000, v123
	global_load_lds_dwordx4 v[34:35], off
	v_lshl_add_u64 v[36:37], v[32:33], 0, v[30:31]
	s_mov_b32 m0, s12
	v_lshlrev_b64 v[38:39], 11, v[38:39]
	v_readfirstlane_b32 s12, v46
	v_add_u32_e32 v46, 0xa000, v111
	global_load_lds_dwordx4 v[36:37], off
	v_lshl_add_u64 v[32:33], v[32:33], 0, v[38:39]
	s_mov_b32 m0, s12
	v_readfirstlane_b32 s12, v46
	global_load_lds_dwordx4 v[32:33], off
	v_lshl_add_u64 v[28:29], v[28:29], 0, s[34:35]
	s_mov_b32 m0, s12
	v_lshl_add_u64 v[24:25], v[24:25], 0, s[34:35]
	global_load_lds_dwordx4 v[28:29], off
	v_add_u32_e32 v28, 0xa000, v122
	v_readlane_b32 s61, v254, 63
	v_readfirstlane_b32 s12, v28
	v_add_u32_e32 v28, 0xe000, v111
	s_mov_b32 m0, s12
	v_readfirstlane_b32 s12, v28
	v_add_u32_e32 v28, 0xe000, v122
	global_load_lds_dwordx4 v[24:25], off
	v_lshl_add_u64 v[24:25], v[34:35], 0, s[34:35]
	s_mov_b32 m0, s12
	v_readfirstlane_b32 s12, v28
	v_add_u32_e32 v28, 0xe000, v123
	global_load_lds_dwordx4 v[24:25], off
	v_lshl_add_u64 v[24:25], v[36:37], 0, s[34:35]
	s_mov_b32 m0, s12
	v_readfirstlane_b32 s12, v28
	global_load_lds_dwordx4 v[24:25], off
	v_lshl_add_u64 v[24:25], v[32:33], 0, s[34:35]
	s_mov_b32 m0, s12
	v_bfe_u32 v28, v40, 1, 3
	global_load_lds_dwordx4 v[24:25], off
	v_mul_i32_i24_e32 v24, 0x60, v44
	v_or_b32_e32 v24, v24, v41
	v_or_b32_e32 v25, v45, v41
	v_bitop3_b32 v29, v42, v28, 3 bitop3:0x6c
	v_lshlrev_b32_e32 v126, 7, v24
	v_bitop3_b32 v24, v43, v28, 4 bitop3:0x36
	v_bitop3_b32 v28, v42, 7, v40 bitop3:0x48
	v_lshlrev_b32_e32 v125, 7, v25
	v_lshlrev_b32_e32 v127, 4, v24
	v_lshl_add_u64 v[24:25], v[38:39], 0, s[16:17]
	v_lshlrev_b32_e32 v28, 4, v28
	v_readlane_b32 s12, v255, 2
	v_or_b32_e32 v24, v24, v28
	v_readlane_b32 s13, v255, 3
	v_mov_b32_e32 v40, 0
	v_lshlrev_b32_e32 v124, 4, v29
	v_lshl_add_u64 v[112:113], s[12:13], 0, v[24:25]
	v_lshl_add_u64 v[24:25], v[30:31], 0, s[16:17]
	v_or_b32_e32 v24, v24, v28
	v_lshl_add_u64 v[114:115], s[12:13], 0, v[24:25]
	v_lshl_add_u64 v[24:25], v[26:27], 0, s[16:17]
	v_or_b32_e32 v24, v24, v28
	v_lshl_add_u64 v[116:117], s[12:13], 0, v[24:25]
	v_lshl_add_u64 v[24:25], v[30:31], 0, s[18:19]
	v_readlane_b32 s12, v255, 30
	v_or_b32_e32 v24, v24, v28
	v_readlane_b32 s13, v255, 31
	s_mov_b64 s[16:17], 0
	v_mov_b32_e32 v41, v40
	v_lshl_add_u64 v[118:119], s[12:13], 0, v[24:25]
	v_lshl_add_u64 v[24:25], v[26:27], 0, s[18:19]
	v_or_b32_e32 v24, v24, v28
	v_lshl_add_u64 v[120:121], s[12:13], 0, v[24:25]
	s_mov_b32 s18, 0
	s_mov_b32 s19, 0
	v_mov_b32_e32 v42, v40
	v_mov_b32_e32 v43, v40
	v_mov_b32_e32 v24, v40
	v_mov_b32_e32 v25, v40
	v_mov_b32_e32 v26, v40
	v_mov_b32_e32 v27, v40
	v_mov_b32_e32 v28, v40
	v_mov_b32_e32 v29, v40
	v_mov_b32_e32 v30, v40
	v_mov_b32_e32 v31, v40
	v_mov_b32_e32 v32, v40
	v_mov_b32_e32 v33, v40
	v_mov_b32_e32 v34, v40
	v_mov_b32_e32 v35, v40
	v_mov_b32_e32 v36, v40
	v_mov_b32_e32 v37, v40
	v_mov_b32_e32 v38, v40
	v_mov_b32_e32 v39, v40
	v_mov_b32_e32 v44, v40
	v_mov_b32_e32 v45, v40
	v_mov_b32_e32 v46, v40
	v_mov_b32_e32 v47, v40
	v_mov_b32_e32 v72, v40
	v_mov_b32_e32 v73, v40
	v_mov_b32_e32 v74, v40
	v_mov_b32_e32 v75, v40
	v_mov_b32_e32 v76, v40
	v_mov_b32_e32 v77, v40
	v_mov_b32_e32 v78, v40
	v_mov_b32_e32 v79, v40
	v_mov_b32_e32 v80, v40
	v_mov_b32_e32 v81, v40
	v_mov_b32_e32 v82, v40
	v_mov_b32_e32 v83, v40
	v_mov_b32_e32 v84, v40
	v_mov_b32_e32 v85, v40
	v_mov_b32_e32 v86, v40
	v_mov_b32_e32 v87, v40
	v_mov_b32_e32 v88, v40
	v_mov_b32_e32 v89, v40
	v_mov_b32_e32 v90, v40
	v_mov_b32_e32 v91, v40
	v_mov_b32_e32 v92, v40
	v_mov_b32_e32 v93, v40
	v_mov_b32_e32 v94, v40
	v_mov_b32_e32 v95, v40
	s_branch .LBB0_1263
.LBB0_1262:
	s_add_i32 s12, s18, 1
	s_cmp_lg_u32 s18, 2
	s_cselect_b32 s18, s12, 0
	s_add_u32 s16, s16, 0x80
	s_addc_u32 s17, s17, 0
	s_add_i32 s19, s19, 1
	s_waitcnt lgkmcnt(9)
	v_mfma_f32_16x16x32_bf16 v[92:95], v[160:163], v[164:167], v[92:95]
	v_mfma_f32_16x16x32_bf16 v[88:91], v[160:163], v[168:171], v[88:91]
	v_mfma_f32_16x16x32_bf16 v[84:87], v[160:163], v[172:175], v[84:87]
	v_mfma_f32_16x16x32_bf16 v[80:83], v[160:163], v[176:179], v[80:83]
	v_mfma_f32_16x16x32_bf16 v[76:79], v[160:163], v[180:183], v[76:79]
	v_mfma_f32_16x16x32_bf16 v[72:75], v[160:163], v[184:187], v[72:75]
	s_waitcnt lgkmcnt(8)
	v_mfma_f32_16x16x32_bf16 v[44:47], v[188:191], v[164:167], v[44:47]
	v_mfma_f32_16x16x32_bf16 v[36:39], v[188:191], v[168:171], v[36:39]
	v_mfma_f32_16x16x32_bf16 v[32:35], v[188:191], v[172:175], v[32:35]
	v_mfma_f32_16x16x32_bf16 v[28:31], v[188:191], v[176:179], v[28:31]
	v_mfma_f32_16x16x32_bf16 v[24:27], v[188:191], v[180:183], v[24:27]
	v_mfma_f32_16x16x32_bf16 v[40:43], v[188:191], v[184:187], v[40:43]
	s_waitcnt lgkmcnt(1)
	v_mfma_f32_16x16x32_bf16 v[92:95], v[192:195], v[198:201], v[92:95]
	v_mfma_f32_16x16x32_bf16 v[88:91], v[192:195], v[202:205], v[88:91]
	v_mfma_f32_16x16x32_bf16 v[84:87], v[192:195], v[206:209], v[84:87]
	v_mfma_f32_16x16x32_bf16 v[80:83], v[192:195], v[210:213], v[80:83]
	v_mfma_f32_16x16x32_bf16 v[76:79], v[192:195], v[214:217], v[76:79]
	v_mfma_f32_16x16x32_bf16 v[72:75], v[192:195], v[218:221], v[72:75]
	s_waitcnt lgkmcnt(0)
	v_mfma_f32_16x16x32_bf16 v[44:47], v[224:227], v[198:201], v[44:47]
	v_mfma_f32_16x16x32_bf16 v[36:39], v[224:227], v[202:205], v[36:39]
	v_mfma_f32_16x16x32_bf16 v[32:35], v[224:227], v[206:209], v[32:35]
	v_mfma_f32_16x16x32_bf16 v[28:31], v[224:227], v[210:213], v[28:31]
	v_mfma_f32_16x16x32_bf16 v[24:27], v[224:227], v[214:217], v[24:27]
	v_mfma_f32_16x16x32_bf16 v[40:43], v[224:227], v[218:221], v[40:43]
	s_cmpk_lg_i32 s16, 0x800
	s_cbranch_scc0 .LBB0_1260

; template <int WN, int WT>
; DEV void gemm_mainloop(const u16* __restrict__ Wt, long ldw, const u16* __restrict__ A, long lda, int K,
;                        char* smem, int tid, f32x4 (&acc)[WN][WT]) {
;     ...
;     __builtin_amdgcn_s_barrier();
;     asm volatile("" ::: "memory");
;     if (kt + 2 < nk) {
;       int nx = cur + 2;
;       if (nx >= 3) nx -= 3;
;       char* nbuf = smem + nx * STG;
;       stage_tile<NR>(Wt, ldw, (kt + 2) * 64, nbuf, tid);
;       stage_tile<TR>(A, lda, (kt + 2) * 64, nbuf + WB, tid);
;     }
;     const char* wb = smem + cur * STG;
;     const char* ab = wb + WB;
; #pragma unroll
;     for (int ks = 0; ks < 2; ++ks) {
;       bf16x8 wf[WN], af[WT];
; #pragma unroll
;       for (int n = 0; n < WN; ++n) wf[n] = lds_frag(wb, wn * (WN * 16) + n * 16 + fr, ks * 4 + fq);
; #pragma unroll
;       for (int t = 0; t < WT; ++t) af[t] = lds_frag(ab, wt * (WT * 16) + t * 16 + fr, ks * 4 + fq);
.LBB0_1267:
	s_barrier
	s_mul_i32 s12, s18, 0xa000
	v_or_b32_e32 v240, s12, v124
	v_or_b32_e32 v241, s12, v127
	v_add_u32_e32 v242, v240, v125
	v_add_u32_e32 v243, v240, v126
	v_add_u32_e32 v244, v241, v125
	v_add_u32_e32 v245, v241, v126
	ds_read_b128 v[160:163], v242
	ds_read_b128 v[164:167], v243 offset:16384
	ds_read_b128 v[168:171], v243 offset:18432
	ds_read_b128 v[172:175], v243 offset:20480
	ds_read_b128 v[176:179], v243 offset:22528
	ds_read_b128 v[180:183], v243 offset:24576
	ds_read_b128 v[184:187], v243 offset:26624
	ds_read_b128 v[188:191], v242 offset:2048
	ds_read_b128 v[192:195], v244
	ds_read_b128 v[198:201], v245 offset:16384
	ds_read_b128 v[202:205], v245 offset:18432
	ds_read_b128 v[206:209], v245 offset:20480
	ds_read_b128 v[210:213], v245 offset:22528
	ds_read_b128 v[214:217], v245 offset:24576
	ds_read_b128 v[218:221], v245 offset:26624
	ds_read_b128 v[224:227], v244 offset:2048
	s_cmp_gt_u32 s19, 13
	s_cbranch_scc1 .LBB0_1262
	s_cmp_gt_i32 s18, 0
	s_cselect_b32 s12, -1, 2
	s_add_i32 s12, s12, s18
	s_mul_i32 s12, s12, 0xa000
	v_add_u32_e32 v130, s12, v111
	v_add_u32_e32 v131, s12, v122
	v_readfirstlane_b32 s13, v130
	v_lshl_add_u64 v[128:129], v[120:121], 0, s[16:17]
	s_mov_b32 m0, s13
	v_readfirstlane_b32 s13, v131
	v_add_u32_e32 v130, 0x4000, v130
	global_load_lds_dwordx4 v[128:129], off
	v_lshl_add_u64 v[128:129], v[118:119], 0, s[16:17]
	s_mov_b32 m0, s13
	v_readfirstlane_b32 s13, v130
	v_add_u32_e32 v130, 0x4000, v131
	global_load_lds_dwordx4 v[128:129], off
	s_mov_b32 m0, s13
	v_readfirstlane_b32 s13, v130
	v_add_u32_e32 v130, s12, v123
	v_lshl_add_u64 v[128:129], v[116:117], 0, s[16:17]
	v_add_u32_e32 v130, 0x4000, v130
	global_load_lds_dwordx4 v[128:129], off
	v_lshl_add_u64 v[128:129], v[114:115], 0, s[16:17]
	s_mov_b32 m0, s13
	v_readfirstlane_b32 s12, v130
	global_load_lds_dwordx4 v[128:129], off
	v_lshl_add_u64 v[128:129], v[112:113], 0, s[16:17]
	s_mov_b32 m0, s12
	s_nop 0
	global_load_lds_dwordx4 v[128:129], off
	s_branch .LBB0_1262
